# bf16-store epilogue (mode 0): one 64-bit mad + chained 64-bit adds for the 8 row-group addresses, each group's two stores issued as soon as its data is converted
# speedup vs baseline: 1.0021x; 1.0021x over previous
; #define GAS __attribute__((address_space(1)))
; DI unsigned pk2(float lo, float hi) { f32x2 v = {lo, hi}; bf16x2_t b = __builtin_convertvector(v, bf16x2_t); return __builtin_bit_cast(unsigned, b); }
;     DI void operator()(const f32x4 (&acc)[2][2][4][2], const Unit& u, int wr, int wc, int fr, int fq) const {
;     ...
;         if (mode == 0) {
;             const int col0 = u.pn * BM + wc * 64 + 8 * fq;
; #pragma unroll
;             for (int ai = 0; ai < 2; ++ai)
; #pragma unroll
;                 for (int m = 0; m < 4; ++m) { bf16_t* rowp = O + (size_t)(row0 + ai * HALF + m * 16) * ldc + col0;
; #pragma unroll
;                     for (int bj = 0; bj < 2; ++bj) { const f32x4 v0 = acc[ai][bj][m][0], v1 = acc[ai][bj][m][1];
;                         u32x4 w; w.x = pk2(v0[0], v0[1]); w.y = pk2(v0[2], v0[3]); w.z = pk2(v1[0], v1[1]); w.w = pk2(v1[2], v1[3]);
;                         *(GAS u32x4*)(rowp + bj * 32) = w; } }
.LBB0_803:
	s_and_b64 vcc, exec, s[0:1]
	s_cbranch_vccz .LBB0_847
	v_cvt_pk_bf16_f32 v118, v118, v119
	v_cvt_pk_bf16_f32 v119, v120, v121
	v_cvt_pk_bf16_f32 v120, v114, v115
	v_cvt_pk_bf16_f32 v102, v102, v103
	v_cvt_pk_bf16_f32 v103, v104, v105
	v_cvt_pk_bf16_f32 v104, v98, v99
	v_cvt_pk_bf16_f32 v86, v86, v87
	v_cvt_pk_bf16_f32 v87, v88, v89
	v_cvt_pk_bf16_f32 v88, v82, v83
	v_cvt_pk_bf16_f32 v70, v70, v71
	v_cvt_pk_bf16_f32 v71, v72, v73
	v_cvt_pk_bf16_f32 v72, v66, v67
	v_cvt_pk_bf16_f32 v54, v54, v55
	v_cvt_pk_bf16_f32 v55, v56, v57
	v_cvt_pk_bf16_f32 v56, v50, v51
	v_cvt_pk_bf16_f32 v38, v38, v39
	v_cvt_pk_bf16_f32 v39, v40, v41
	v_cvt_pk_bf16_f32 v40, v34, v35
	v_cvt_pk_bf16_f32 v22, v22, v23
	v_cvt_pk_bf16_f32 v23, v24, v25
	v_cvt_pk_bf16_f32 v24, v18, v19
	v_ashrrev_i32_e32 v179, 31, v178
	v_mad_i64_i32 v[130:131], s[0:1], v176, s50, 0
	s_lshl_b32 s40, s50, 5
	s_mov_b32 s41, 0
	v_lshlrev_b64 v[132:133], 1, v[178:179]
	v_lshl_add_u64 v[130:131], v[130:131], 1, s[30:31]
	v_lshl_add_u64 v[130:131], v[130:131], 0, v[132:133]
	v_cvt_pk_bf16_f32 v122, v122, v123
	v_cvt_pk_bf16_f32 v123, v124, v125
	v_cvt_pk_bf16_f32 v124, v126, v127
	v_cvt_pk_bf16_f32 v125, v128, v129
	v_cvt_pk_bf16_f32 v121, v116, v117
	global_store_dwordx4 v[130:131], v[122:125], off
	global_store_dwordx4 v[130:131], v[118:121], off offset:64
	v_lshl_add_u64 v[114:115], v[130:131], 0, s[40:41]
	v_cvt_pk_bf16_f32 v110, v110, v111
	v_cvt_pk_bf16_f32 v111, v112, v113
	v_cvt_pk_bf16_f32 v112, v106, v107
	v_cvt_pk_bf16_f32 v113, v108, v109
	v_cvt_pk_bf16_f32 v105, v100, v101
	global_store_dwordx4 v[114:115], v[110:113], off
	global_store_dwordx4 v[114:115], v[102:105], off offset:64
	v_lshl_add_u64 v[98:99], v[114:115], 0, s[40:41]
	v_cvt_pk_bf16_f32 v94, v94, v95
	v_cvt_pk_bf16_f32 v95, v96, v97
	v_cvt_pk_bf16_f32 v96, v90, v91
	v_cvt_pk_bf16_f32 v97, v92, v93
	v_cvt_pk_bf16_f32 v89, v84, v85
	global_store_dwordx4 v[98:99], v[94:97], off
	global_store_dwordx4 v[98:99], v[86:89], off offset:64
	v_lshl_add_u64 v[82:83], v[98:99], 0, s[40:41]
	v_cvt_pk_bf16_f32 v78, v78, v79
	v_cvt_pk_bf16_f32 v79, v80, v81
	v_cvt_pk_bf16_f32 v80, v74, v75
	v_cvt_pk_bf16_f32 v81, v76, v77
	v_cvt_pk_bf16_f32 v73, v68, v69
	global_store_dwordx4 v[82:83], v[78:81], off
	global_store_dwordx4 v[82:83], v[70:73], off offset:64
	s_mul_i32 s40, s50, 0xa0
	v_lshl_add_u64 v[66:67], v[82:83], 0, s[40:41]
	s_lshl_b32 s40, s50, 5
	v_cvt_pk_bf16_f32 v62, v62, v63
	v_cvt_pk_bf16_f32 v63, v64, v65
	v_cvt_pk_bf16_f32 v64, v58, v59
	v_cvt_pk_bf16_f32 v65, v60, v61
	v_cvt_pk_bf16_f32 v57, v52, v53
	global_store_dwordx4 v[66:67], v[62:65], off
	global_store_dwordx4 v[66:67], v[54:57], off offset:64
	v_lshl_add_u64 v[50:51], v[66:67], 0, s[40:41]
	v_cvt_pk_bf16_f32 v46, v46, v47
	v_cvt_pk_bf16_f32 v47, v48, v49
	v_cvt_pk_bf16_f32 v48, v42, v43
	v_cvt_pk_bf16_f32 v49, v44, v45
	v_cvt_pk_bf16_f32 v41, v36, v37
	global_store_dwordx4 v[50:51], v[46:49], off
	global_store_dwordx4 v[50:51], v[38:41], off offset:64
	v_lshl_add_u64 v[34:35], v[50:51], 0, s[40:41]
	v_cvt_pk_bf16_f32 v30, v30, v31
	v_cvt_pk_bf16_f32 v31, v32, v33
	v_cvt_pk_bf16_f32 v32, v26, v27
	v_cvt_pk_bf16_f32 v33, v28, v29
	v_cvt_pk_bf16_f32 v25, v20, v21
	global_store_dwordx4 v[34:35], v[30:33], off
	global_store_dwordx4 v[34:35], v[22:25], off offset:64
	v_lshl_add_u64 v[18:19], v[34:35], 0, s[40:41]
	v_cvt_pk_bf16_f32 v14, v14, v15
	v_cvt_pk_bf16_f32 v15, v16, v17
	v_cvt_pk_bf16_f32 v16, v10, v11
	v_cvt_pk_bf16_f32 v17, v12, v13
	v_cvt_pk_bf16_f32 v6, v6, v7
	v_cvt_pk_bf16_f32 v7, v8, v9
	v_cvt_pk_bf16_f32 v8, v2, v3
	v_cvt_pk_bf16_f32 v9, v4, v5
	global_store_dwordx4 v[18:19], v[14:17], off
	global_store_dwordx4 v[18:19], v[6:9], off offset:64
	s_and_b64 vcc, exec, s[4:5]
	s_mov_b64 s[0:1], -1
	s_cbranch_vccnz .LBB0_780
	s_branch .LBB0_848
